# late attention reuses early attention code (late copy deleted); grid-barrier non-leaders poll TOPGEN directly
# speedup vs baseline: 1.0019x; 1.0019x over previous
; __device__ __forceinline__ unsigned xb_ld(unsigned* p)              { return __hip_atomic_load(p, __ATOMIC_RELAXED, __HIP_MEMORY_SCOPE_AGENT); }
; __device__ __forceinline__ unsigned xb_add(unsigned* p, unsigned v) { return __hip_atomic_fetch_add(p, v, __ATOMIC_RELAXED, __HIP_MEMORY_SCOPE_AGENT); }
; #define XB_SPIN(cond, bar) do { unsigned _sp = 0; while (cond) { __builtin_amdgcn_s_sleep(1); \
;     if ((++_sp & 255u) == 0u) { if (xb_ld(&(bar)[XB_TMO])) break; if (_sp > XB_SPIN_CAP) { atomicAdd(&(bar)[XB_TMO], 1u); break; } } } } while (0)
; __device__ __forceinline__ void xcd_barrier(const XcdBarrier& b) {
;     ...
;         const unsigned old = xb_add(&bar[XB_XSUB(b.x)], 1u);
;         const unsigned gen = old / nloc;
;         if (old + 1u == (gen + 1u) * nloc) {
;             __builtin_amdgcn_fence(__ATOMIC_RELEASE, "agent");
;             asm volatile("s_waitcnt vmcnt(0)" ::: "memory");
;             const unsigned og = xb_add(&bar[XB_TOP], 1u);
;             const unsigned tg = og / nx;
;             if (og + 1u == (tg + 1u) * nx) xb_add(&bar[XB_TOPGEN], 1u);
;             else XB_SPIN(xb_ld(&bar[XB_TOPGEN]) == tg, bar);
;             __builtin_amdgcn_fence(__ATOMIC_ACQUIRE, "agent");
;             xb_add(&bar[XB_XGEN(b.x)], 1u);
;             asm volatile("s_waitcnt vmcnt(0)" ::: "memory");
;         } else {
;             XB_SPIN(xb_ld(&bar[XB_XGEN(b.x)]) == gen, bar);
;             __builtin_amdgcn_fence(__ATOMIC_ACQUIRE, "agent");
;             asm volatile("s_waitcnt vmcnt(0)" ::: "memory");
;         }
.LBB0_42:
	s_lshl_b32 s4, s84, 8
	s_add_u32 s4, s22, s4
	s_addc_u32 s5, s23, 0
	v_mov_b32_e32 v2, 0x1000
	v_mov_b32_e32 v4, 1
	global_atomic_add v4, v2, v4, s[4:5] offset:1024 sc0
	v_cvt_f32_u32_e32 v2, v3
	v_sub_u32_e32 v5, 0, v3
	v_rcp_iflag_f32_e32 v2, v2
	s_nop 0
	v_mul_f32_e32 v2, 0x4f7ffffe, v2
	v_cvt_u32_f32_e32 v2, v2
	v_mul_lo_u32 v5, v5, v2
	v_mul_hi_u32 v5, v2, v5
	v_add_u32_e32 v2, v2, v5
	s_waitcnt vmcnt(0)
	v_mul_hi_u32 v2, v4, v2
	v_mul_lo_u32 v5, v2, v3
	v_sub_u32_e32 v5, v4, v5
	v_add_u32_e32 v6, 1, v2
	v_cmp_ge_u32_e32 vcc, v5, v3
	v_add_u32_e32 v4, 1, v4
	s_nop 0
	v_cndmask_b32_e32 v2, v2, v6, vcc
	v_sub_u32_e32 v6, v5, v3
	v_cndmask_b32_e32 v5, v5, v6, vcc
	v_add_u32_e32 v6, 1, v2
	v_cmp_ge_u32_e32 vcc, v5, v3
	s_nop 1
	v_cndmask_b32_e32 v2, v2, v6, vcc
	v_mul_lo_u32 v5, v3, v2
	v_add_u32_e32 v3, v5, v3
	v_cmp_ne_u32_e32 vcc, v4, v3
	s_and_saveexec_b64 s[6:7], vcc
	s_xor_b64 s[6:7], exec, s[6:7]
	s_cbranch_execz .LBB0_56
	s_waitcnt lgkmcnt(0)
	v_mov_b32_e32 v1, 0x3500
	global_load_dword v1, v1, s[22:23] sc1
	s_add_u32 s14, s22, 0x3500
	s_addc_u32 s15, s23, 0
	s_waitcnt vmcnt(0)
	v_cmp_eq_u32_e32 vcc, v1, v2
	s_and_saveexec_b64 s[10:11], vcc
	s_cbranch_execz .LBB0_55
	s_add_u32 s12, s24, 0x3e00200
	s_addc_u32 s13, s25, 0
	s_mov_b32 s36, 1
	s_mov_b64 s[16:17], 0
	v_mov_b32_e32 v1, 0
	s_branch .LBB0_46

; __device__ __forceinline__ unsigned xb_ld(unsigned* p)              { return __hip_atomic_load(p, __ATOMIC_RELAXED, __HIP_MEMORY_SCOPE_AGENT); }
; __device__ __forceinline__ unsigned xb_add(unsigned* p, unsigned v) { return __hip_atomic_fetch_add(p, v, __ATOMIC_RELAXED, __HIP_MEMORY_SCOPE_AGENT); }
; #define XB_SPIN(cond, bar) do { unsigned _sp = 0; while (cond) { __builtin_amdgcn_s_sleep(1); \
;     if ((++_sp & 255u) == 0u) { if (xb_ld(&(bar)[XB_TMO])) break; if (_sp > XB_SPIN_CAP) { atomicAdd(&(bar)[XB_TMO], 1u); break; } } } } while (0)
; __device__ __forceinline__ void xcd_barrier(const XcdBarrier& b) {
;     ...
;         const unsigned old = xb_add(&bar[XB_XSUB(b.x)], 1u);
;         const unsigned gen = old / nloc;
;         if (old + 1u == (gen + 1u) * nloc) {
;             __builtin_amdgcn_fence(__ATOMIC_RELEASE, "agent");
;             asm volatile("s_waitcnt vmcnt(0)" ::: "memory");
;             const unsigned og = xb_add(&bar[XB_TOP], 1u);
;             const unsigned tg = og / nx;
;             if (og + 1u == (tg + 1u) * nx) xb_add(&bar[XB_TOPGEN], 1u);
;             else XB_SPIN(xb_ld(&bar[XB_TOPGEN]) == tg, bar);
;             __builtin_amdgcn_fence(__ATOMIC_ACQUIRE, "agent");
;             xb_add(&bar[XB_XGEN(b.x)], 1u);
;             asm volatile("s_waitcnt vmcnt(0)" ::: "memory");
;         } else {
;             XB_SPIN(xb_ld(&bar[XB_XGEN(b.x)]) == gen, bar);
;             __builtin_amdgcn_fence(__ATOMIC_ACQUIRE, "agent");
;             asm volatile("s_waitcnt vmcnt(0)" ::: "memory");
;         }
.LBB0_150:
	s_lshl_b32 s4, s84, 8
	s_add_u32 s4, s22, s4
	s_addc_u32 s5, s23, 0
	v_mov_b32_e32 v2, 0x1000
	v_mov_b32_e32 v4, 1
	global_atomic_add v4, v2, v4, s[4:5] offset:1024 sc0
	v_cvt_f32_u32_e32 v2, v3
	v_sub_u32_e32 v5, 0, v3
	v_rcp_iflag_f32_e32 v2, v2
	s_nop 0
	v_mul_f32_e32 v2, 0x4f7ffffe, v2
	v_cvt_u32_f32_e32 v2, v2
	v_mul_lo_u32 v5, v5, v2
	v_mul_hi_u32 v5, v2, v5
	v_add_u32_e32 v2, v2, v5
	s_waitcnt vmcnt(0)
	v_mul_hi_u32 v2, v4, v2
	v_mul_lo_u32 v5, v2, v3
	v_sub_u32_e32 v5, v4, v5
	v_add_u32_e32 v6, 1, v2
	v_cmp_ge_u32_e32 vcc, v5, v3
	v_add_u32_e32 v4, 1, v4
	s_nop 0
	v_cndmask_b32_e32 v2, v2, v6, vcc
	v_sub_u32_e32 v6, v5, v3
	v_cndmask_b32_e32 v5, v5, v6, vcc
	v_add_u32_e32 v6, 1, v2
	v_cmp_ge_u32_e32 vcc, v5, v3
	s_nop 1
	v_cndmask_b32_e32 v2, v2, v6, vcc
	v_mul_lo_u32 v5, v3, v2
	v_add_u32_e32 v3, v5, v3
	v_cmp_ne_u32_e32 vcc, v4, v3
	s_and_saveexec_b64 s[6:7], vcc
	s_xor_b64 s[6:7], exec, s[6:7]
	s_cbranch_execz .LBB0_164
	s_waitcnt lgkmcnt(0)
	v_mov_b32_e32 v1, 0x3500
	global_load_dword v1, v1, s[22:23] sc1
	s_add_u32 s14, s22, 0x3500
	s_addc_u32 s15, s23, 0
	s_waitcnt vmcnt(0)
	v_cmp_eq_u32_e32 vcc, v1, v2
	s_and_saveexec_b64 s[10:11], vcc
	s_cbranch_execz .LBB0_163
	s_add_u32 s12, s24, 0x3e00200
	s_addc_u32 s13, s25, 0
	s_mov_b32 s46, 1
	s_mov_b64 s[16:17], 0
	v_mov_b32_e32 v1, 0
	s_branch .LBB0_154

; __device__ __forceinline__ unsigned xb_ld(unsigned* p)              { return __hip_atomic_load(p, __ATOMIC_RELAXED, __HIP_MEMORY_SCOPE_AGENT); }
; __device__ __forceinline__ unsigned xb_add(unsigned* p, unsigned v) { return __hip_atomic_fetch_add(p, v, __ATOMIC_RELAXED, __HIP_MEMORY_SCOPE_AGENT); }
; #define XB_SPIN(cond, bar) do { unsigned _sp = 0; while (cond) { __builtin_amdgcn_s_sleep(1); \
;     if ((++_sp & 255u) == 0u) { if (xb_ld(&(bar)[XB_TMO])) break; if (_sp > XB_SPIN_CAP) { atomicAdd(&(bar)[XB_TMO], 1u); break; } } } } while (0)
; __device__ __forceinline__ void xcd_barrier(const XcdBarrier& b) {
;     ...
;         const unsigned old = xb_add(&bar[XB_XSUB(b.x)], 1u);
;         const unsigned gen = old / nloc;
;         if (old + 1u == (gen + 1u) * nloc) {
;             __builtin_amdgcn_fence(__ATOMIC_RELEASE, "agent");
;             asm volatile("s_waitcnt vmcnt(0)" ::: "memory");
;             const unsigned og = xb_add(&bar[XB_TOP], 1u);
;             const unsigned tg = og / nx;
;             if (og + 1u == (tg + 1u) * nx) xb_add(&bar[XB_TOPGEN], 1u);
;             else XB_SPIN(xb_ld(&bar[XB_TOPGEN]) == tg, bar);
;             __builtin_amdgcn_fence(__ATOMIC_ACQUIRE, "agent");
;             xb_add(&bar[XB_XGEN(b.x)], 1u);
;             asm volatile("s_waitcnt vmcnt(0)" ::: "memory");
;         } else {
;             XB_SPIN(xb_ld(&bar[XB_XGEN(b.x)]) == gen, bar);
;             __builtin_amdgcn_fence(__ATOMIC_ACQUIRE, "agent");
;             asm volatile("s_waitcnt vmcnt(0)" ::: "memory");
;         }
.LBB0_411:
	s_lshl_b32 s4, s84, 8
	s_add_u32 s4, s22, s4
	s_addc_u32 s5, s23, 0
	v_mov_b32_e32 v2, 0x1000
	v_mov_b32_e32 v4, 1
	global_atomic_add v4, v2, v4, s[4:5] offset:1024 sc0
	v_cvt_f32_u32_e32 v2, v3
	v_sub_u32_e32 v5, 0, v3
	v_rcp_iflag_f32_e32 v2, v2
	s_nop 0
	v_mul_f32_e32 v2, 0x4f7ffffe, v2
	v_cvt_u32_f32_e32 v2, v2
	v_mul_lo_u32 v5, v5, v2
	v_mul_hi_u32 v5, v2, v5
	v_add_u32_e32 v2, v2, v5
	s_waitcnt vmcnt(0)
	v_mul_hi_u32 v2, v4, v2
	v_mul_lo_u32 v5, v2, v3
	v_sub_u32_e32 v5, v4, v5
	v_add_u32_e32 v6, 1, v2
	v_cmp_ge_u32_e32 vcc, v5, v3
	v_add_u32_e32 v4, 1, v4
	s_nop 0
	v_cndmask_b32_e32 v2, v2, v6, vcc
	v_sub_u32_e32 v6, v5, v3
	v_cndmask_b32_e32 v5, v5, v6, vcc
	v_add_u32_e32 v6, 1, v2
	v_cmp_ge_u32_e32 vcc, v5, v3
	s_nop 1
	v_cndmask_b32_e32 v2, v2, v6, vcc
	v_mul_lo_u32 v5, v3, v2
	v_add_u32_e32 v3, v5, v3
	v_cmp_ne_u32_e32 vcc, v4, v3
	s_and_saveexec_b64 s[6:7], vcc
	s_xor_b64 s[6:7], exec, s[6:7]
	s_cbranch_execz .LBB0_425
	s_waitcnt lgkmcnt(0)
	v_mov_b32_e32 v1, 0x3500
	global_load_dword v1, v1, s[22:23] sc1
	s_add_u32 s14, s22, 0x3500
	s_addc_u32 s15, s23, 0
	s_waitcnt vmcnt(0)
	v_cmp_eq_u32_e32 vcc, v1, v2
	s_and_saveexec_b64 s[10:11], vcc
	s_cbranch_execz .LBB0_424
	s_add_u32 s12, s24, 0x3e00200
	s_addc_u32 s13, s25, 0
	s_mov_b32 s56, 1
	s_mov_b64 s[16:17], 0
	v_mov_b32_e32 v1, 0
	s_branch .LBB0_415

; #define ATT_LOAD(KS, VS, c, set) do { const bf16_t* s_ = ((c) < 4) ? (KS) + (size_t)(64 * (c)) * 256 : (VS) + (size_t)(64 * ((c) - 4)) * 256; \
;         _Pragma("unroll") for (int it = 0; it < 4; ++it) stg[set][it] = *(const u32x4*)(s_ + (size_t)(16 * it) * 256); } while (0)
; __device__ __forceinline__ void attn_phase(LAS unsigned char* lds, const bf16_t* PROJ, const bf16_t* KM, const bf16_t* VT, bf16_t* Y, float* SS, int bx, int G, int tid) {
;     const int lane = tid & 63, wid = __builtin_amdgcn_readfirstlane(tid >> 6), fr = lane & 15, fq = lane >> 4;
;     int u = bx; if (u >= 512) return;
;     const int srow = tid >> 5, sc16 = tid & 31, sdst = srow * ATT_ROWB + ((sc16 ^ srow) << 4);
;     const int vs_ = sc16 & 3, vblk4_ = (sc16 >> 2) * 4;
;     const int rho0_ = 16 * ((srow >> 2) & 1) + 4 * (srow >> 3) + (srow & 3), vsw_ = rho0_ & 15;
;     const int vdst0 = rho0_ * ATT_ROWB + (((vblk4_ + ((2 * vs_) & 3)) ^ vsw_) << 4) + 8 * (vs_ >> 1);
;     const int frd = fr * ATT_ROWB + ((fq ^ fr) << 4);
;     int T0 = (u >> 2) * 128, h = u & 3, b = T0 / SEQ;
;     const bf16_t* ksrc = KM + ((size_t)(b * 4 + h) * 256 + srow) * 256 + sc16 * 8;
;     const bf16_t* vsrc = VT + ((size_t)(h * 4 + b) * 256 + srow) * 256 + sc16 * 8;
;     bf16x8 qf[8];
;     { const bf16_t* qp = PJ(PROJ, T0 + wid * 16 + fr, COL_Q + h * 256 + fq * 8);
; #pragma unroll
;       for (int ks = 0; ks < 8; ++ks) qf[ks] = *(const bf16x8*)(qp + ks * 512); }
;     u32x4 stg[2][4];
;     ...
;     ATT_LOAD(ksrc, vsrc, 0, 0); ATT_LOAD(ksrc, vsrc, 1, 1); ATT_WRITE(0, 0, false); __syncthreads();
.Lattn_entry:
	s_cmpk_gt_i32 s2, 0x1ff
	v_readfirstlane_b32 s0, v0
	s_cbranch_scc1 .Lattn_exit
	s_lshl_b32 s1, s2, 5
	s_and_b32 s95, s1, 0xffffff80
	s_bfe_i32 s1, s2, 0x1001a
	s_lshr_b32 s1, s1, 20
	s_add_i32 s1, s95, s1
	s_ashr_i32 s1, s1, 12
	s_lshl_b32 s4, s1, 2
	s_or_b32 s4, s4, s74
	s_ashr_i32 s5, s4, 31
	s_lshl_b64 s[4:5], s[4:5], 17
	s_lshl_b32 s10, s74, 2
	v_lshrrev_b32_e32 v3, 5, v0
	s_add_u32 s4, s40, s4
	v_and_b32_e32 v1, 15, v0
	v_lshrrev_b32_e32 v2, 4, v0
	v_lshrrev_b32_e32 v6, 3, v0
	v_lshrrev_b32_e32 v7, 6, v0
	v_lshlrev_b32_e32 v178, 9, v3
	v_mov_b32_e32 v179, 0
	s_addc_u32 s5, s41, s5
	v_bfe_u32 v67, v0, 4, 2
	s_waitcnt lgkmcnt(0)
	v_and_b32_e32 v4, 31, v0
	v_bitop3_b32 v5, v0, v3, 31 bitop3:0x6c
	v_and_b32_e32 v6, 16, v6
	v_and_b32_e32 v7, 4, v7
	v_bfe_u32 v8, v0, 5, 2
	v_bitop3_b32 v2, v2, v1, 3 bitop3:0x6c
	v_lshl_add_u64 v[190:191], s[4:5], 0, v[178:179]
	s_ashr_i32 s5, s0, 2
	v_lshlrev_b32_e32 v70, 4, v5
	v_and_b32_e32 v5, 28, v0
	v_or3_b32 v72, v7, v8, v6
	v_lshlrev_b32_e32 v6, 1, v0
	v_lshlrev_b32_e32 v74, 4, v2
	v_lshlrev_b32_e32 v75, 3, v67
	v_lshlrev_b32_e32 v2, 5, v0
	s_movk_i32 s11, 0x1e0
	v_lshlrev_b32_e32 v68, 4, v4
	v_mov_b32_e32 v69, v179
	s_add_i32 s0, s5, s95
	v_and_or_b32 v5, v6, 2, v5
	v_and_or_b32 v66, v2, s11, v75
	v_lshl_add_u64 v[30:31], v[190:191], 0, v[68:69]
	s_ashr_i32 s0, s0, 4
	s_movk_i32 s21, 0x2000
	v_bitop3_b32 v71, v7, v5, v8 bitop3:0x36
	v_lshlrev_b32_e32 v2, 1, v66
	v_mov_b32_e32 v3, v179
	s_add_i32 s4, s1, s10
	s_ashr_i32 s1, s0, 31
	v_add_co_u32_e32 v8, vcc, s21, v30
	v_lshl_add_u64 v[2:3], s[6:7], 0, v[2:3]
	s_movk_i32 s20, 0x4000
	s_lshl_b64 s[0:1], s[0:1], 13
	v_addc_co_u32_e32 v9, vcc, 0, v31, vcc
	v_lshl_add_u64 v[6:7], v[2:3], 0, s[0:1]
	s_mov_b64 s[10:11], 0xa000000
	v_add_co_u32_e32 v12, vcc, s20, v30
	v_lshlrev_b32_e32 v5, 2, v0
	v_lshl_add_u64 v[10:11], v[6:7], 0, s[10:11]
	v_addc_co_u32_e32 v13, vcc, 0, v31, vcc
	s_movk_i32 s58, 0x6000
	v_and_b32_e32 v73, 8, v5
	v_lshlrev_b32_e32 v254, 3, v4
	global_load_dwordx4 v[2:5], v[10:11], off offset:1024
	global_load_dwordx4 v[42:45], v[30:31], off
	global_load_dwordx4 v[54:57], v[8:9], off
	global_load_dwordx4 v[58:61], v[12:13], off
	v_add_co_u32_e32 v8, vcc, s58, v30
	s_mov_b32 s0, 0xa001000
	s_nop 0
	v_addc_co_u32_e32 v9, vcc, 0, v31, vcc
	v_add_co_u32_e32 v32, vcc, s0, v6
	s_mov_b32 s59, 0x8000
	s_nop 0
	v_addc_co_u32_e32 v33, vcc, 0, v7, vcc
	v_add_co_u32_e32 v34, vcc, s59, v30
	global_load_dwordx4 v[62:65], v[8:9], off
	s_nop 0
	v_addc_co_u32_e32 v35, vcc, 0, v31, vcc
	s_mov_b32 s60, 0xa000
	v_add_co_u32_e32 v38, vcc, s60, v30
	s_mov_b32 s61, 0xc000
	s_nop 0
	v_addc_co_u32_e32 v39, vcc, 0, v31, vcc
	global_load_dwordx4 v[6:9], v[10:11], off offset:2048
	s_nop 0
	global_load_dwordx4 v[10:13], v[10:11], off offset:3072
	s_nop 0
	global_load_dwordx4 v[14:17], v[32:33], off
	global_load_dwordx4 v[18:21], v[32:33], off offset:1024
	global_load_dwordx4 v[22:25], v[32:33], off offset:2048
	global_load_dwordx4 v[26:29], v[32:33], off offset:3072
	v_add_co_u32_e32 v46, vcc, s61, v30
	s_mov_b32 s70, 0xe000
	s_nop 0
	v_addc_co_u32_e32 v47, vcc, 0, v31, vcc
	v_add_co_u32_e32 v50, vcc, s70, v30
	global_load_dwordx4 v[34:37], v[34:35], off
	s_nop 0
	v_addc_co_u32_e32 v51, vcc, 0, v31, vcc
	global_load_dwordx4 v[38:41], v[38:39], off
	s_nop 0
	global_load_dwordx4 v[46:49], v[46:47], off
	s_nop 0
	global_load_dwordx4 v[30:33], v[32:33], off offset:-4096
	s_nop 0
	global_load_dwordx4 v[50:53], v[50:51], off
	v_add3_u32 v195, 0, v70, v178
	s_waitcnt vmcnt(0)
	ds_write_b128 v195, v[42:45]
	ds_write_b128 v195, v[54:57] offset:8192
	ds_write_b128 v195, v[58:61] offset:16384
	ds_write_b128 v195, v[62:65] offset:24576
	v_mbcnt_lo_u32_b32 v42, -1, 0
	v_mbcnt_hi_u32_b32 v42, -1, v42
	v_and_b32_e32 v44, 64, v42
	v_xor_b32_e32 v43, 16, v42
	v_add_u32_e32 v44, 64, v44
	v_cmp_lt_i32_e32 vcc, v43, v44
	v_lshlrev_b32_e32 v76, 9, v1
	v_lshlrev_b32_e32 v77, 4, v71
	v_lshl_add_u64 v[70:71], s[42:43], 0, v[178:179]
	s_movk_i32 s14, 0xc0
	v_cndmask_b32_e32 v43, v42, v43, vcc
	v_lshl_add_u64 v[204:205], v[70:71], 0, v[68:69]
	v_lshl_or_b32 v69, v72, 9, v73
	s_movk_i32 s12, 0x80
	v_bitop3_b32 v200, v74, s14, v76 bitop3:0x36
	s_movk_i32 s14, 0x140
	v_lshlrev_b32_e32 v215, 2, v43
	v_xor_b32_e32 v43, 32, v42
	v_bitop3_b32 v201, v74, s14, v76 bitop3:0x36
	s_movk_i32 s14, 0x180
	v_bitop3_b32 v208, v69, s12, v77 bitop3:0x36
	s_and_b32 s80, s5, -16
	v_cmp_lt_i32_e32 vcc, v43, v44
	s_lshl_b32 s5, s5, 7
	v_lshl_or_b32 v68, v1, 5, v75
	v_or_b32_e32 v196, v69, v77
	v_bitop3_b32 v199, v74, s12, v76 bitop3:0x36
	v_bitop3_b32 v202, v74, s14, v76 bitop3:0x36
	s_movk_i32 s14, 0x1c0
	v_add_u32_e32 v209, 0x1000, v208
	s_movk_i32 s12, 0x4010
	v_add_u32_e32 v213, 0x5000, v208
	v_cndmask_b32_e32 v42, v42, v43, vcc
	s_and_b32 s81, s5, 0x3800
	s_add_i32 s5, s2, s3
	v_or_b32_e32 v194, v74, v76
	s_mov_b32 s13, 0
	v_lshl_add_u64 v[184:185], s[40:41], 0, v[178:179]
	v_lshlrev_b32_e32 v197, 4, v67
	v_cmp_eq_u32_e64 s[0:1], 0, v67
	v_bitop3_b32 v198, v74, 64, v76 bitop3:0x36
	v_bitop3_b32 v203, v74, s14, v76 bitop3:0x36
	s_mov_b32 s71, 0x10000
	s_mov_b32 s72, 0x12000
	s_mov_b32 s73, 0x14000
	s_mov_b32 s75, 0x16000
	s_mov_b32 s76, 0x18000
	s_mov_b32 s77, 0x1a000
	v_add_u32_e32 v189, 0x1a000, v195
	s_mov_b32 s78, 0x1c000
	s_mov_b32 s79, 0x1e000
	v_add_u32_e32 v206, 0x1e000, v195
	v_bitop3_b32 v207, v69, 16, v77 bitop3:0x36
	v_xor_b32_e32 v210, 16, v209
	v_or_b32_e32 v211, 0x4000, v196
	v_bitop3_b32 v212, v69, s12, v77 bitop3:0x36
	v_xor_b32_e32 v214, 16, v213
	v_lshlrev_b32_e32 v216, 2, v42
	s_lshl_b32 s82, s5, 5
	s_lshl_b32 s83, s3, 5
	v_lshlrev_b32_e32 v186, 1, v68
	s_mov_b64 s[14:15], 0xc000000
	s_add_i32 s86, 0, 0x10000
	s_add_i32 s87, 0, 0x18000
	s_mov_b32 s88, 0xff61b1e6
	s_brev_b32 s89, 48
	v_lshlrev_b32_e32 v188, 1, v66
	s_movk_i32 s90, 0x3c0
	s_mov_b32 s12, s74
	s_mov_b32 s91, s2
	s_waitcnt lgkmcnt(0)
	s_barrier
	s_branch .LBB0_449

; __global__ void __launch_bounds__(NTHR, 2) mk_fwd(Args a) {
;     ...
;         const bool late_attn = ((bx >> 3) & 1) != 0;
;         if (!late_attn) attn_phase(lds, Proj, Kmat, VTm, Yb, SS, bx, G, tid);
;         pool_phase(lds, Proj, PoolWT, pool_scale, Yb, SS, bx, G);
;         sgu_phase(lds, Proj, VST, SguW, sgu_ln_g, sgu_ln_b, sgu_b, Yb, SS, bx, G);
;         if (late_attn) { int tid2 = threadIdx.x, bx2 = blockIdx.x; asm volatile("" : "+v"(tid2), "+s"(bx2));
;             attn_phase(lds, Proj, Kmat, VTm, Yb, SS, bx2, G, tid2); }
.Lattn_exit:
	s_and_b64 vcc, exec, s[56:57]
	s_cbranch_vccnz .LBB0_678

; __global__ void __launch_bounds__(NTHR, 2) mk_fwd(Args a) {
;     ...
;         sgu_phase(lds, Proj, VST, SguW, sgu_ln_g, sgu_ln_b, sgu_b, Yb, SS, bx, G);
;         if (late_attn) { int tid2 = threadIdx.x, bx2 = blockIdx.x; asm volatile("" : "+v"(tid2), "+s"(bx2));
;             attn_phase(lds, Proj, Kmat, VTm, Yb, SS, bx2, G, tid2); }
.LBB0_664:
	s_andn2_b64 vcc, exec, s[56:57]
	s_cbranch_vccnz .LBB0_679
	s_waitcnt vmcnt(0) lgkmcnt(0)
	s_lshl_b32 s0, s74, 23
	s_add_u32 s6, s36, s0
	s_addc_u32 s7, s37, 0
	s_branch .Lattn_entry

; __device__ __forceinline__ unsigned xb_ld(unsigned* p)              { return __hip_atomic_load(p, __ATOMIC_RELAXED, __HIP_MEMORY_SCOPE_AGENT); }
; __device__ __forceinline__ unsigned xb_add(unsigned* p, unsigned v) { return __hip_atomic_fetch_add(p, v, __ATOMIC_RELAXED, __HIP_MEMORY_SCOPE_AGENT); }
; #define XB_SPIN(cond, bar) do { unsigned _sp = 0; while (cond) { __builtin_amdgcn_s_sleep(1); \
;     if ((++_sp & 255u) == 0u) { if (xb_ld(&(bar)[XB_TMO])) break; if (_sp > XB_SPIN_CAP) { atomicAdd(&(bar)[XB_TMO], 1u); break; } } } } while (0)
; __device__ __forceinline__ void xcd_barrier(const XcdBarrier& b) {
;     ...
;         const unsigned old = xb_add(&bar[XB_XSUB(b.x)], 1u);
;         const unsigned gen = old / nloc;
;         if (old + 1u == (gen + 1u) * nloc) {
;             __builtin_amdgcn_fence(__ATOMIC_RELEASE, "agent");
;             asm volatile("s_waitcnt vmcnt(0)" ::: "memory");
;             const unsigned og = xb_add(&bar[XB_TOP], 1u);
;             const unsigned tg = og / nx;
;             if (og + 1u == (tg + 1u) * nx) xb_add(&bar[XB_TOPGEN], 1u);
;             else XB_SPIN(xb_ld(&bar[XB_TOPGEN]) == tg, bar);
;             __builtin_amdgcn_fence(__ATOMIC_ACQUIRE, "agent");
;             xb_add(&bar[XB_XGEN(b.x)], 1u);
;             asm volatile("s_waitcnt vmcnt(0)" ::: "memory");
;         } else {
;             XB_SPIN(xb_ld(&bar[XB_XGEN(b.x)]) == gen, bar);
;             __builtin_amdgcn_fence(__ATOMIC_ACQUIRE, "agent");
;             asm volatile("s_waitcnt vmcnt(0)" ::: "memory");
;         }
.LBB0_696:
	s_lshl_b32 s4, s84, 8
	s_add_u32 s4, s22, s4
	s_addc_u32 s5, s23, 0
	v_mov_b32_e32 v2, 0x1000
	v_mov_b32_e32 v4, 1
	global_atomic_add v4, v2, v4, s[4:5] offset:1024 sc0
	v_cvt_f32_u32_e32 v2, v3
	v_sub_u32_e32 v5, 0, v3
	v_rcp_iflag_f32_e32 v2, v2
	s_nop 0
	v_mul_f32_e32 v2, 0x4f7ffffe, v2
	v_cvt_u32_f32_e32 v2, v2
	v_mul_lo_u32 v5, v5, v2
	v_mul_hi_u32 v5, v2, v5
	v_add_u32_e32 v2, v2, v5
	s_waitcnt vmcnt(0)
	v_mul_hi_u32 v2, v4, v2
	v_mul_lo_u32 v5, v2, v3
	v_sub_u32_e32 v5, v4, v5
	v_add_u32_e32 v6, 1, v2
	v_cmp_ge_u32_e32 vcc, v5, v3
	v_add_u32_e32 v4, 1, v4
	s_nop 0
	v_cndmask_b32_e32 v2, v2, v6, vcc
	v_sub_u32_e32 v6, v5, v3
	v_cndmask_b32_e32 v5, v5, v6, vcc
	v_add_u32_e32 v6, 1, v2
	v_cmp_ge_u32_e32 vcc, v5, v3
	s_nop 1
	v_cndmask_b32_e32 v2, v2, v6, vcc
	v_mul_lo_u32 v5, v3, v2
	v_add_u32_e32 v3, v5, v3
	v_cmp_ne_u32_e32 vcc, v4, v3
	s_and_saveexec_b64 s[6:7], vcc
	s_xor_b64 s[6:7], exec, s[6:7]
	s_cbranch_execz .LBB0_710
	s_waitcnt lgkmcnt(0)
	v_mov_b32_e32 v1, 0x3500
	global_load_dword v1, v1, s[22:23] sc1
	s_add_u32 s12, s22, 0x3500
	s_addc_u32 s13, s23, 0
	s_waitcnt vmcnt(0)
	v_cmp_eq_u32_e32 vcc, v1, v2
	s_and_saveexec_b64 s[8:9], vcc
	s_cbranch_execz .LBB0_709
	s_add_u32 s10, s24, 0x3e00200
	s_addc_u32 s11, s25, 0
	s_mov_b32 s38, 1
	s_mov_b64 s[14:15], 0
	v_mov_b32_e32 v1, 0
	s_branch .LBB0_700

; __device__ __forceinline__ unsigned xb_ld(unsigned* p)              { return __hip_atomic_load(p, __ATOMIC_RELAXED, __HIP_MEMORY_SCOPE_AGENT); }
; __device__ __forceinline__ unsigned xb_add(unsigned* p, unsigned v) { return __hip_atomic_fetch_add(p, v, __ATOMIC_RELAXED, __HIP_MEMORY_SCOPE_AGENT); }
; #define XB_SPIN(cond, bar) do { unsigned _sp = 0; while (cond) { __builtin_amdgcn_s_sleep(1); \
;     if ((++_sp & 255u) == 0u) { if (xb_ld(&(bar)[XB_TMO])) break; if (_sp > XB_SPIN_CAP) { atomicAdd(&(bar)[XB_TMO], 1u); break; } } } } while (0)
; __device__ __forceinline__ void xcd_barrier(const XcdBarrier& b) {
;     ...
;         const unsigned old = xb_add(&bar[XB_XSUB(b.x)], 1u);
;         const unsigned gen = old / nloc;
;         if (old + 1u == (gen + 1u) * nloc) {
;             __builtin_amdgcn_fence(__ATOMIC_RELEASE, "agent");
;             asm volatile("s_waitcnt vmcnt(0)" ::: "memory");
;             const unsigned og = xb_add(&bar[XB_TOP], 1u);
;             const unsigned tg = og / nx;
;             if (og + 1u == (tg + 1u) * nx) xb_add(&bar[XB_TOPGEN], 1u);
;             else XB_SPIN(xb_ld(&bar[XB_TOPGEN]) == tg, bar);
;             __builtin_amdgcn_fence(__ATOMIC_ACQUIRE, "agent");
;             xb_add(&bar[XB_XGEN(b.x)], 1u);
;             asm volatile("s_waitcnt vmcnt(0)" ::: "memory");
;         } else {
;             XB_SPIN(xb_ld(&bar[XB_XGEN(b.x)]) == gen, bar);
;             __builtin_amdgcn_fence(__ATOMIC_ACQUIRE, "agent");
;             asm volatile("s_waitcnt vmcnt(0)" ::: "memory");
;         }
.LBB0_803:
	s_lshl_b32 s4, s84, 8
	s_add_u32 s4, s22, s4
	s_addc_u32 s5, s23, 0
	v_mov_b32_e32 v1, 0x1000
	v_mov_b32_e32 v3, 1
	global_atomic_add v3, v1, v3, s[4:5] offset:1024 sc0
	v_cvt_f32_u32_e32 v1, v2
	v_sub_u32_e32 v4, 0, v2
	v_rcp_iflag_f32_e32 v1, v1
	s_nop 0
	v_mul_f32_e32 v1, 0x4f7ffffe, v1
	v_cvt_u32_f32_e32 v1, v1
	v_mul_lo_u32 v4, v4, v1
	v_mul_hi_u32 v4, v1, v4
	v_add_u32_e32 v1, v1, v4
	s_waitcnt vmcnt(0)
	v_mul_hi_u32 v1, v3, v1
	v_mul_lo_u32 v4, v1, v2
	v_sub_u32_e32 v4, v3, v4
	v_add_u32_e32 v5, 1, v1
	v_cmp_ge_u32_e32 vcc, v4, v2
	v_add_u32_e32 v3, 1, v3
	s_nop 0
	v_cndmask_b32_e32 v1, v1, v5, vcc
	v_sub_u32_e32 v5, v4, v2
	v_cndmask_b32_e32 v4, v4, v5, vcc
	v_add_u32_e32 v5, 1, v1
	v_cmp_ge_u32_e32 vcc, v4, v2
	s_nop 1
	v_cndmask_b32_e32 v1, v1, v5, vcc
	v_mul_lo_u32 v4, v2, v1
	v_add_u32_e32 v2, v4, v2
	v_cmp_ne_u32_e32 vcc, v3, v2
	s_and_saveexec_b64 s[6:7], vcc
	s_xor_b64 s[6:7], exec, s[6:7]
	s_cbranch_execz .LBB0_817
	s_waitcnt lgkmcnt(0)
	v_mov_b32_e32 v0, 0x3500
	global_load_dword v0, v0, s[22:23] sc1
	s_add_u32 s14, s22, 0x3500
	s_addc_u32 s15, s23, 0
	s_waitcnt vmcnt(0)
	v_cmp_eq_u32_e32 vcc, v0, v1
	s_and_saveexec_b64 s[8:9], vcc
	s_cbranch_execz .LBB0_816
	s_add_u32 s10, s24, 0x3e00200
	s_addc_u32 s11, s25, 0
	s_mov_b32 s34, 1
	s_mov_b64 s[16:17], 0
	v_mov_b32_e32 v0, 0
	s_branch .LBB0_807
